# v34: v28 + dead s_mov/s_nop leftovers removed from the w_in V-tile epilogue (129 instructions)
# speedup vs baseline: 1.0052x; 1.0052x over previous
; __device__ __forceinline__ bf16_t f2bf1(float f) { return (bf16_t)(cvt_pk_bf16(f, 0.f) & 0xffffu); }
;     __device__ __forceinline__ void operator()(const f32x4 (&acc)[2][2][4][2], const Unit& u, int wr, int wc, int fr, int fq) const {
;     ...
;         } else if (pn == 2) {
;             bf16_t* VTG = (bf16_t*)(ws + WS_VTG);
;             float* ovp = out + O_WVP + (size_t)l * 131072; float* ovs = out + O_WVS + (size_t)l * 524288;
; #pragma unroll
;             for (int ai = 0; ai < 2; ++ai)
; #pragma unroll
;                 for (int m = 0; m < 4; ++m) {
;                     int row = u.pm * BM + ai * HALF + wr * 64 + m * 16 + fr;
;                     asm volatile("" : "+v"(row));
;                     const float rs = R[ai * HALF + wr * 64 + m * 16 + fr];
;                     const int sb = (row - E_MP) >> 6, st = (row - E_MP) & 63, pb = row >> 11, pt = row & 2047;
; #pragma unroll
;                     for (int bj = 0; bj < 2; ++bj) {
;                         const f32x4 v0 = acc[ai][bj][m][0] * rs, v1 = acc[ai][bj][m][1] * rs;
;                         const int c0 = (wc - 2) * 64 + bj * 32 + 8 * fq;
;                         bf16_t* vp = VTG + (size_t)c0 * E_MT + row;
; #pragma unroll
;                         for (int j = 0; j < 4; ++j) { vp[(size_t)j * E_MT] = f2bf1(v0[j]); vp[(size_t)(4 + j) * E_MT] = f2bf1(v1[j]); }
;                         if (is_s) { float* d = ovs + ((size_t)(sb * 128 + 64 + st) * 128 + c0); __builtin_nontemporal_store(v0, (f32x4*)d); __builtin_nontemporal_store(v1, (f32x4*)(d + 4)); }
;                         else if (pt >= 1920) { float* d = ovp + ((size_t)(pb * 128 + (pt - 1920)) * 128 + c0); __builtin_nontemporal_store(v0, (f32x4*)d); __builtin_nontemporal_store(v1, (f32x4*)(d + 4)); }
;                     }
;                 }
.LBB0_626:
	s_andn2_b64 vcc, exec, s[0:1]
	s_cbranch_vccnz .LBB0_660
	v_and_b32_e32 v223, 1, v222
	v_cmp_eq_u32_e32 vcc, 1, v223
	v_mov_b32_e32 v220, 0x5040100
	v_mov_b32_e32 v250, 0x3020706
	s_mov_b32 s101, 0
	v_cndmask_b32_e32 v220, v220, v250, vcc
	v_mov_b32_e32 v250, 0x8ffe
	v_cndmask_b32_e32 v223, v185, v250, vcc
	v_lshl_add_u32 v170, s53, 8, v153
	v_mov_b32_e32 v128, v170
	s_movk_i32 s0, 0x77f
	v_ashrrev_i32_e32 v129, 31, v128
	v_lshl_add_u64 v[138:139], v[128:129], 1, s[42:43]
	v_ashrrev_i32_e32 v129, 4, v128
	v_and_b32_e32 v130, 0x7ff, v128
	v_and_b32_e32 v129, 0xffffff80, v129
	s_movk_i32 s4, 0xf880
	ds_read_b32 v136, v165
	v_and_b32_e32 v132, 63, v128
	v_cmp_lt_u32_e64 s[0:1], s0, v130
	v_add3_u32 v130, v130, v129, s4
	v_lshlrev_b32_e32 v128, 1, v128
	s_movk_i32 s4, 0xff80
	v_and_or_b32 v128, v128, s4, v132
	v_add_u32_e32 v128, 0xffff8040, v128
	v_ashrrev_i32_e32 v131, 31, v130
	v_ashrrev_i32_e32 v129, 31, v128
	v_lshl_add_u64 v[172:173], v[138:139], 0, v[156:157]
	v_lshlrev_b64 v[130:131], 9, v[130:131]
	v_lshlrev_b64 v[128:129], 9, v[128:129]
	v_lshl_add_u64 v[140:141], s[26:27], 0, v[130:131]
	v_lshl_add_u64 v[142:143], s[30:31], 0, v[128:129]
	s_waitcnt lgkmcnt(0)
	v_pk_mul_f32 v[130:131], v[126:127], v[136:137] op_sel_hi:[1,0]
	v_pk_mul_f32 v[128:129], v[124:125], v[136:137] op_sel_hi:[1,0]
	v_pk_mul_f32 v[134:135], v[122:123], v[136:137] op_sel_hi:[1,0]
	v_pk_mul_f32 v[132:133], v[120:121], v[136:137] op_sel_hi:[1,0]
	s_or_b64 s[0:1], s[38:39], s[0:1]
	s_nop 0
	v_cndmask_b32_e64 v141, v141, v143, s[38:39]
	s_nop 0
	v_cndmask_b32_e64 v140, v140, v142, s[38:39]
	s_nop 0
	v_lshlrev_b32_e32 v184, 2, v154
	v_cvt_pk_bf16_f32 v190, v128, v129
	v_cvt_pk_bf16_f32 v191, v130, v131
	v_cvt_pk_bf16_f32 v217, v132, v133
	v_cvt_pk_bf16_f32 v226, v134, v135
	v_add_co_u32_e32 v172, vcc, v223, v172
	s_nop 1
	v_addc_co_u32_e32 v173, vcc, 0, v173, vcc
	v_mov_b32_dpp v250, v190 quad_perm:[1,0,3,2] row_mask:0xf bank_mask:0xf
	v_perm_b32 v190, v250, v190, v220
	global_store_dword v[172:173], v190, off
	s_mov_b32 s100, 0x12000
	v_lshl_add_u64 v[174:175], v[172:173], 0, s[100:101]
	v_mov_b32_dpp v250, v191 quad_perm:[1,0,3,2] row_mask:0xf bank_mask:0xf
	v_perm_b32 v191, v250, v191, v220
	global_store_dword v[174:175], v191, off
	s_mov_b32 s100, 0x24000
	v_lshl_add_u64 v[174:175], v[172:173], 0, s[100:101]
	v_mov_b32_dpp v250, v217 quad_perm:[1,0,3,2] row_mask:0xf bank_mask:0xf
	v_perm_b32 v217, v250, v217, v220
	global_store_dword v[174:175], v217, off
	s_mov_b32 s100, 0x36000
	v_lshl_add_u64 v[174:175], v[172:173], 0, s[100:101]
	v_mov_b32_dpp v250, v226 quad_perm:[1,0,3,2] row_mask:0xf bank_mask:0xf
	v_perm_b32 v226, v250, v226, v220
	global_store_dword v[174:175], v226, off
	s_and_saveexec_b64 s[4:5], s[0:1]
	s_cbranch_execz .LBB0_629
	v_lshl_add_u64 v[142:143], v[140:141], 0, v[184:185]
	global_store_dwordx4 v[142:143], v[128:131], off offset:-512 nt
	global_store_dwordx4 v[142:143], v[132:135], off offset:-496 nt
.LBB0_629:
	s_or_b64 exec, exec, s[4:5]
	v_mov_b32_e32 v137, v136
	v_mov_b32_e32 v132, v136
	v_mov_b32_e32 v133, v136
	v_pk_mul_f32 v[130:131], v[118:119], v[132:133]
	v_pk_mul_f32 v[128:129], v[116:117], v[136:137]
	v_pk_mul_f32 v[134:135], v[114:115], v[132:133]
	v_pk_mul_f32 v[132:133], v[112:113], v[136:137]
	v_lshl_add_u64 v[136:137], v[138:139], 0, v[158:159]
	s_nop 1
	s_nop 1
	s_nop 0
	v_cvt_pk_bf16_f32 v190, v128, v129
	v_cvt_pk_bf16_f32 v191, v130, v131
	v_cvt_pk_bf16_f32 v217, v132, v133
	v_cvt_pk_bf16_f32 v226, v134, v135
	v_add_co_u32_e32 v136, vcc, v223, v136
	s_nop 1
	v_addc_co_u32_e32 v137, vcc, 0, v137, vcc
	v_mov_b32_dpp v250, v190 quad_perm:[1,0,3,2] row_mask:0xf bank_mask:0xf
	v_perm_b32 v190, v250, v190, v220
	global_store_dword v[136:137], v190, off
	s_mov_b32 s100, 0x12000
	v_lshl_add_u64 v[138:139], v[136:137], 0, s[100:101]
	v_mov_b32_dpp v250, v191 quad_perm:[1,0,3,2] row_mask:0xf bank_mask:0xf
	v_perm_b32 v191, v250, v191, v220
	global_store_dword v[138:139], v191, off
	s_mov_b32 s100, 0x24000
	v_lshl_add_u64 v[138:139], v[136:137], 0, s[100:101]
	v_mov_b32_dpp v250, v217 quad_perm:[1,0,3,2] row_mask:0xf bank_mask:0xf
	v_perm_b32 v217, v250, v217, v220
	global_store_dword v[138:139], v217, off
	s_mov_b32 s100, 0x36000
	v_lshl_add_u64 v[138:139], v[136:137], 0, s[100:101]
	v_mov_b32_dpp v250, v226 quad_perm:[1,0,3,2] row_mask:0xf bank_mask:0xf
	v_perm_b32 v226, v250, v226, v220
	global_store_dword v[138:139], v226, off
	v_lshlrev_b32_e32 v136, 2, v164
	s_and_saveexec_b64 s[4:5], s[0:1]
	s_cbranch_execz .LBB0_631
	v_mov_b32_e32 v137, v185
	v_lshl_add_u64 v[138:139], v[140:141], 0, v[136:137]
	global_store_dwordx4 v[138:139], v[128:131], off offset:-512 nt
	global_store_dwordx4 v[138:139], v[132:135], off offset:-496 nt
; __device__ __forceinline__ bf16_t f2bf1(float f) { return (bf16_t)(cvt_pk_bf16(f, 0.f) & 0xffffu); }
;     __device__ __forceinline__ void operator()(const f32x4 (&acc)[2][2][4][2], const Unit& u, int wr, int wc, int fr, int fq) const {
;     ...
;         } else if (pn == 2) {
;             bf16_t* VTG = (bf16_t*)(ws + WS_VTG);
;             float* ovp = out + O_WVP + (size_t)l * 131072; float* ovs = out + O_WVS + (size_t)l * 524288;
; #pragma unroll
;             for (int ai = 0; ai < 2; ++ai)
; #pragma unroll
;                 for (int m = 0; m < 4; ++m) {
;                     int row = u.pm * BM + ai * HALF + wr * 64 + m * 16 + fr;
;                     asm volatile("" : "+v"(row));
;                     const float rs = R[ai * HALF + wr * 64 + m * 16 + fr];
;                     const int sb = (row - E_MP) >> 6, st = (row - E_MP) & 63, pb = row >> 11, pt = row & 2047;
; #pragma unroll
;                     for (int bj = 0; bj < 2; ++bj) {
;                         const f32x4 v0 = acc[ai][bj][m][0] * rs, v1 = acc[ai][bj][m][1] * rs;
;                         const int c0 = (wc - 2) * 64 + bj * 32 + 8 * fq;
;                         bf16_t* vp = VTG + (size_t)c0 * E_MT + row;
; #pragma unroll
;                         for (int j = 0; j < 4; ++j) { vp[(size_t)j * E_MT] = f2bf1(v0[j]); vp[(size_t)(4 + j) * E_MT] = f2bf1(v1[j]); }
;                         if (is_s) { float* d = ovs + ((size_t)(sb * 128 + 64 + st) * 128 + c0); __builtin_nontemporal_store(v0, (f32x4*)d); __builtin_nontemporal_store(v1, (f32x4*)(d + 4)); }
;                         else if (pt >= 1920) { float* d = ovp + ((size_t)(pb * 128 + (pt - 1920)) * 128 + c0); __builtin_nontemporal_store(v0, (f32x4*)d); __builtin_nontemporal_store(v1, (f32x4*)(d + 4)); }
;                     }
;                 }
.LBB0_631:
	s_or_b64 exec, exec, s[4:5]
	v_or_b32_e32 v128, 16, v170
	s_movk_i32 s0, 0x77f
	v_ashrrev_i32_e32 v129, 31, v128
	v_lshl_add_u64 v[140:141], v[128:129], 1, s[42:43]
	v_ashrrev_i32_e32 v129, 4, v128
	v_and_b32_e32 v130, 0x7ff, v128
	v_and_b32_e32 v129, 0xffffff80, v129
	s_movk_i32 s4, 0xf880
	ds_read_b32 v138, v165 offset:64
	v_and_b32_e32 v132, 63, v128
	v_cmp_lt_u32_e64 s[0:1], s0, v130
	v_add3_u32 v130, v130, v129, s4
	v_lshlrev_b32_e32 v128, 1, v128
	s_movk_i32 s4, 0xff80
	v_and_or_b32 v128, v128, s4, v132
	v_add_u32_e32 v128, 0xffff8040, v128
	v_ashrrev_i32_e32 v129, 31, v128
	v_lshl_add_u64 v[174:175], v[140:141], 0, v[156:157]
	v_lshlrev_b64 v[128:129], 9, v[128:129]
	v_lshl_add_u64 v[172:173], s[30:31], 0, v[128:129]
	s_waitcnt lgkmcnt(0)
	v_pk_mul_f32 v[128:129], v[108:109], v[138:139] op_sel_hi:[1,0]
	v_pk_mul_f32 v[132:133], v[104:105], v[138:139] op_sel_hi:[1,0]
	v_ashrrev_i32_e32 v131, 31, v130
	v_lshlrev_b64 v[130:131], 9, v[130:131]
	s_nop 0
	v_lshl_add_u64 v[142:143], s[26:27], 0, v[130:131]
	v_pk_mul_f32 v[130:131], v[110:111], v[138:139] op_sel_hi:[1,0]
	v_pk_mul_f32 v[134:135], v[106:107], v[138:139] op_sel_hi:[1,0]
	s_or_b64 s[0:1], s[38:39], s[0:1]
	s_nop 0
	v_cndmask_b32_e64 v143, v143, v173, s[38:39]
	s_nop 0
	v_cndmask_b32_e64 v142, v142, v172, s[38:39]
	s_nop 0
	v_cvt_pk_bf16_f32 v190, v128, v129
	v_cvt_pk_bf16_f32 v191, v130, v131
	v_cvt_pk_bf16_f32 v217, v132, v133
	v_cvt_pk_bf16_f32 v226, v134, v135
	v_add_co_u32_e32 v174, vcc, v223, v174
	s_nop 1
	v_addc_co_u32_e32 v175, vcc, 0, v175, vcc
	v_mov_b32_dpp v250, v190 quad_perm:[1,0,3,2] row_mask:0xf bank_mask:0xf
	v_perm_b32 v190, v250, v190, v220
	global_store_dword v[174:175], v190, off
	s_mov_b32 s100, 0x12000
	v_lshl_add_u64 v[176:177], v[174:175], 0, s[100:101]
	v_mov_b32_dpp v250, v191 quad_perm:[1,0,3,2] row_mask:0xf bank_mask:0xf
	v_perm_b32 v191, v250, v191, v220
	global_store_dword v[176:177], v191, off
	s_mov_b32 s100, 0x24000
	v_lshl_add_u64 v[176:177], v[174:175], 0, s[100:101]
	v_mov_b32_dpp v250, v217 quad_perm:[1,0,3,2] row_mask:0xf bank_mask:0xf
	v_perm_b32 v217, v250, v217, v220
	global_store_dword v[176:177], v217, off
	s_mov_b32 s100, 0x36000
	v_lshl_add_u64 v[176:177], v[174:175], 0, s[100:101]
	v_mov_b32_dpp v250, v226 quad_perm:[1,0,3,2] row_mask:0xf bank_mask:0xf
	v_perm_b32 v226, v250, v226, v220
	global_store_dword v[176:177], v226, off
	s_and_saveexec_b64 s[4:5], s[0:1]
	s_cbranch_execz .LBB0_633
	v_lshl_add_u64 v[172:173], v[142:143], 0, v[184:185]
	global_store_dwordx4 v[172:173], v[128:131], off offset:-512 nt
	global_store_dwordx4 v[172:173], v[132:135], off offset:-496 nt
.LBB0_633:
	s_or_b64 exec, exec, s[4:5]
	v_mov_b32_e32 v139, v138
	v_mov_b32_e32 v132, v138
	v_mov_b32_e32 v133, v138
	v_pk_mul_f32 v[130:131], v[102:103], v[132:133]
	v_pk_mul_f32 v[128:129], v[100:101], v[138:139]
	v_pk_mul_f32 v[134:135], v[98:99], v[132:133]
	v_pk_mul_f32 v[132:133], v[96:97], v[138:139]
	v_lshl_add_u64 v[138:139], v[140:141], 0, v[158:159]
	s_nop 1
	s_nop 1
	s_nop 0
	v_cvt_pk_bf16_f32 v190, v128, v129
	v_cvt_pk_bf16_f32 v191, v130, v131
	v_cvt_pk_bf16_f32 v217, v132, v133
	v_cvt_pk_bf16_f32 v226, v134, v135
	v_add_co_u32_e32 v138, vcc, v223, v138
	s_nop 1
	v_addc_co_u32_e32 v139, vcc, 0, v139, vcc
	v_mov_b32_dpp v250, v190 quad_perm:[1,0,3,2] row_mask:0xf bank_mask:0xf
	v_perm_b32 v190, v250, v190, v220
	global_store_dword v[138:139], v190, off
	s_mov_b32 s100, 0x12000
	v_lshl_add_u64 v[140:141], v[138:139], 0, s[100:101]
	v_mov_b32_dpp v250, v191 quad_perm:[1,0,3,2] row_mask:0xf bank_mask:0xf
	v_perm_b32 v191, v250, v191, v220
	global_store_dword v[140:141], v191, off
	s_mov_b32 s100, 0x24000
	v_lshl_add_u64 v[140:141], v[138:139], 0, s[100:101]
	v_mov_b32_dpp v250, v217 quad_perm:[1,0,3,2] row_mask:0xf bank_mask:0xf
	v_perm_b32 v217, v250, v217, v220
	global_store_dword v[140:141], v217, off
	s_mov_b32 s100, 0x36000
	v_lshl_add_u64 v[140:141], v[138:139], 0, s[100:101]
	v_mov_b32_dpp v250, v226 quad_perm:[1,0,3,2] row_mask:0xf bank_mask:0xf
	v_perm_b32 v226, v250, v226, v220
	global_store_dword v[140:141], v226, off
	s_and_saveexec_b64 s[4:5], s[0:1]
	s_cbranch_execz .LBB0_635
	v_mov_b32_e32 v137, v185
	v_lshl_add_u64 v[138:139], v[142:143], 0, v[136:137]
	global_store_dwordx4 v[138:139], v[128:131], off offset:-512 nt
	global_store_dwordx4 v[138:139], v[132:135], off offset:-496 nt
; __device__ __forceinline__ bf16_t f2bf1(float f) { return (bf16_t)(cvt_pk_bf16(f, 0.f) & 0xffffu); }
;     __device__ __forceinline__ void operator()(const f32x4 (&acc)[2][2][4][2], const Unit& u, int wr, int wc, int fr, int fq) const {
;     ...
;         } else if (pn == 2) {
;             bf16_t* VTG = (bf16_t*)(ws + WS_VTG);
;             float* ovp = out + O_WVP + (size_t)l * 131072; float* ovs = out + O_WVS + (size_t)l * 524288;
; #pragma unroll
;             for (int ai = 0; ai < 2; ++ai)
; #pragma unroll
;                 for (int m = 0; m < 4; ++m) {
;                     int row = u.pm * BM + ai * HALF + wr * 64 + m * 16 + fr;
;                     asm volatile("" : "+v"(row));
;                     const float rs = R[ai * HALF + wr * 64 + m * 16 + fr];
;                     const int sb = (row - E_MP) >> 6, st = (row - E_MP) & 63, pb = row >> 11, pt = row & 2047;
; #pragma unroll
;                     for (int bj = 0; bj < 2; ++bj) {
;                         const f32x4 v0 = acc[ai][bj][m][0] * rs, v1 = acc[ai][bj][m][1] * rs;
;                         const int c0 = (wc - 2) * 64 + bj * 32 + 8 * fq;
;                         bf16_t* vp = VTG + (size_t)c0 * E_MT + row;
; #pragma unroll
;                         for (int j = 0; j < 4; ++j) { vp[(size_t)j * E_MT] = f2bf1(v0[j]); vp[(size_t)(4 + j) * E_MT] = f2bf1(v1[j]); }
;                         if (is_s) { float* d = ovs + ((size_t)(sb * 128 + 64 + st) * 128 + c0); __builtin_nontemporal_store(v0, (f32x4*)d); __builtin_nontemporal_store(v1, (f32x4*)(d + 4)); }
;                         else if (pt >= 1920) { float* d = ovp + ((size_t)(pb * 128 + (pt - 1920)) * 128 + c0); __builtin_nontemporal_store(v0, (f32x4*)d); __builtin_nontemporal_store(v1, (f32x4*)(d + 4)); }
;                     }
;                 }
.LBB0_635:
	s_or_b64 exec, exec, s[4:5]
	v_or_b32_e32 v128, 32, v170
	s_movk_i32 s0, 0x77f
	v_ashrrev_i32_e32 v129, 31, v128
	v_lshl_add_u64 v[140:141], v[128:129], 1, s[42:43]
	v_ashrrev_i32_e32 v129, 4, v128
	v_and_b32_e32 v130, 0x7ff, v128
	v_and_b32_e32 v129, 0xffffff80, v129
	s_movk_i32 s4, 0xf880
	ds_read_b32 v138, v165 offset:128
	v_and_b32_e32 v132, 63, v128
	v_cmp_lt_u32_e64 s[0:1], s0, v130
	v_add3_u32 v130, v130, v129, s4
	v_lshlrev_b32_e32 v128, 1, v128
	s_movk_i32 s4, 0xff80
	v_and_or_b32 v128, v128, s4, v132
	v_add_u32_e32 v128, 0xffff8040, v128
	v_ashrrev_i32_e32 v129, 31, v128
	v_lshl_add_u64 v[174:175], v[140:141], 0, v[156:157]
	v_lshlrev_b64 v[128:129], 9, v[128:129]
	v_lshl_add_u64 v[172:173], s[30:31], 0, v[128:129]
	s_waitcnt lgkmcnt(0)
	v_pk_mul_f32 v[128:129], v[92:93], v[138:139] op_sel_hi:[1,0]
	v_pk_mul_f32 v[132:133], v[88:89], v[138:139] op_sel_hi:[1,0]
	v_ashrrev_i32_e32 v131, 31, v130
	v_lshlrev_b64 v[130:131], 9, v[130:131]
	s_nop 0
	v_lshl_add_u64 v[142:143], s[26:27], 0, v[130:131]
	v_pk_mul_f32 v[130:131], v[94:95], v[138:139] op_sel_hi:[1,0]
	v_pk_mul_f32 v[134:135], v[90:91], v[138:139] op_sel_hi:[1,0]
	s_or_b64 s[0:1], s[38:39], s[0:1]
	s_nop 0
	v_cndmask_b32_e64 v143, v143, v173, s[38:39]
	s_nop 0
	v_cndmask_b32_e64 v142, v142, v172, s[38:39]
	s_nop 0
	v_cvt_pk_bf16_f32 v190, v128, v129
	v_cvt_pk_bf16_f32 v191, v130, v131
	v_cvt_pk_bf16_f32 v217, v132, v133
	v_cvt_pk_bf16_f32 v226, v134, v135
	v_add_co_u32_e32 v174, vcc, v223, v174
	s_nop 1
	v_addc_co_u32_e32 v175, vcc, 0, v175, vcc
	v_mov_b32_dpp v250, v190 quad_perm:[1,0,3,2] row_mask:0xf bank_mask:0xf
	v_perm_b32 v190, v250, v190, v220
	global_store_dword v[174:175], v190, off
	s_mov_b32 s100, 0x12000
	v_lshl_add_u64 v[176:177], v[174:175], 0, s[100:101]
	v_mov_b32_dpp v250, v191 quad_perm:[1,0,3,2] row_mask:0xf bank_mask:0xf
	v_perm_b32 v191, v250, v191, v220
	global_store_dword v[176:177], v191, off
	s_mov_b32 s100, 0x24000
	v_lshl_add_u64 v[176:177], v[174:175], 0, s[100:101]
	v_mov_b32_dpp v250, v217 quad_perm:[1,0,3,2] row_mask:0xf bank_mask:0xf
	v_perm_b32 v217, v250, v217, v220
	global_store_dword v[176:177], v217, off
	s_mov_b32 s100, 0x36000
	v_lshl_add_u64 v[176:177], v[174:175], 0, s[100:101]
	v_mov_b32_dpp v250, v226 quad_perm:[1,0,3,2] row_mask:0xf bank_mask:0xf
	v_perm_b32 v226, v250, v226, v220
	global_store_dword v[176:177], v226, off
	s_and_saveexec_b64 s[4:5], s[0:1]
	s_cbranch_execz .LBB0_637
	v_lshl_add_u64 v[172:173], v[142:143], 0, v[184:185]
	global_store_dwordx4 v[172:173], v[128:131], off offset:-512 nt
	global_store_dwordx4 v[172:173], v[132:135], off offset:-496 nt
.LBB0_637:
	s_or_b64 exec, exec, s[4:5]
	v_mov_b32_e32 v139, v138
	v_mov_b32_e32 v132, v138
	v_mov_b32_e32 v133, v138
	v_pk_mul_f32 v[130:131], v[86:87], v[132:133]
	v_pk_mul_f32 v[128:129], v[84:85], v[138:139]
	v_pk_mul_f32 v[134:135], v[82:83], v[132:133]
	v_pk_mul_f32 v[132:133], v[80:81], v[138:139]
	v_lshl_add_u64 v[138:139], v[140:141], 0, v[158:159]
	s_nop 1
	s_nop 1
	s_nop 0
	v_cvt_pk_bf16_f32 v190, v128, v129
	v_cvt_pk_bf16_f32 v191, v130, v131
	v_cvt_pk_bf16_f32 v217, v132, v133
	v_cvt_pk_bf16_f32 v226, v134, v135
	v_add_co_u32_e32 v138, vcc, v223, v138
	s_nop 1
	v_addc_co_u32_e32 v139, vcc, 0, v139, vcc
	v_mov_b32_dpp v250, v190 quad_perm:[1,0,3,2] row_mask:0xf bank_mask:0xf
	v_perm_b32 v190, v250, v190, v220
	global_store_dword v[138:139], v190, off
	s_mov_b32 s100, 0x12000
	v_lshl_add_u64 v[140:141], v[138:139], 0, s[100:101]
	v_mov_b32_dpp v250, v191 quad_perm:[1,0,3,2] row_mask:0xf bank_mask:0xf
	v_perm_b32 v191, v250, v191, v220
	global_store_dword v[140:141], v191, off
	s_mov_b32 s100, 0x24000
	v_lshl_add_u64 v[140:141], v[138:139], 0, s[100:101]
	v_mov_b32_dpp v250, v217 quad_perm:[1,0,3,2] row_mask:0xf bank_mask:0xf
	v_perm_b32 v217, v250, v217, v220
	global_store_dword v[140:141], v217, off
	s_mov_b32 s100, 0x36000
	v_lshl_add_u64 v[140:141], v[138:139], 0, s[100:101]
	v_mov_b32_dpp v250, v226 quad_perm:[1,0,3,2] row_mask:0xf bank_mask:0xf
	v_perm_b32 v226, v250, v226, v220
	global_store_dword v[140:141], v226, off
	s_and_saveexec_b64 s[4:5], s[0:1]
	s_cbranch_execz .LBB0_639
	v_mov_b32_e32 v137, v185
	v_lshl_add_u64 v[138:139], v[142:143], 0, v[136:137]
	global_store_dwordx4 v[138:139], v[128:131], off offset:-512 nt
	global_store_dwordx4 v[138:139], v[132:135], off offset:-496 nt
; __device__ __forceinline__ bf16_t f2bf1(float f) { return (bf16_t)(cvt_pk_bf16(f, 0.f) & 0xffffu); }
;     __device__ __forceinline__ void operator()(const f32x4 (&acc)[2][2][4][2], const Unit& u, int wr, int wc, int fr, int fq) const {
;     ...
;         } else if (pn == 2) {
;             bf16_t* VTG = (bf16_t*)(ws + WS_VTG);
;             float* ovp = out + O_WVP + (size_t)l * 131072; float* ovs = out + O_WVS + (size_t)l * 524288;
; #pragma unroll
;             for (int ai = 0; ai < 2; ++ai)
; #pragma unroll
;                 for (int m = 0; m < 4; ++m) {
;                     int row = u.pm * BM + ai * HALF + wr * 64 + m * 16 + fr;
;                     asm volatile("" : "+v"(row));
;                     const float rs = R[ai * HALF + wr * 64 + m * 16 + fr];
;                     const int sb = (row - E_MP) >> 6, st = (row - E_MP) & 63, pb = row >> 11, pt = row & 2047;
; #pragma unroll
;                     for (int bj = 0; bj < 2; ++bj) {
;                         const f32x4 v0 = acc[ai][bj][m][0] * rs, v1 = acc[ai][bj][m][1] * rs;
;                         const int c0 = (wc - 2) * 64 + bj * 32 + 8 * fq;
;                         bf16_t* vp = VTG + (size_t)c0 * E_MT + row;
; #pragma unroll
;                         for (int j = 0; j < 4; ++j) { vp[(size_t)j * E_MT] = f2bf1(v0[j]); vp[(size_t)(4 + j) * E_MT] = f2bf1(v1[j]); }
;                         if (is_s) { float* d = ovs + ((size_t)(sb * 128 + 64 + st) * 128 + c0); __builtin_nontemporal_store(v0, (f32x4*)d); __builtin_nontemporal_store(v1, (f32x4*)(d + 4)); }
;                         else if (pt >= 1920) { float* d = ovp + ((size_t)(pb * 128 + (pt - 1920)) * 128 + c0); __builtin_nontemporal_store(v0, (f32x4*)d); __builtin_nontemporal_store(v1, (f32x4*)(d + 4)); }
;                     }
;                 }
.LBB0_639:
	s_or_b64 exec, exec, s[4:5]
	v_or_b32_e32 v128, 48, v170
	s_movk_i32 s0, 0x77f
	v_ashrrev_i32_e32 v129, 31, v128
	v_lshl_add_u64 v[140:141], v[128:129], 1, s[42:43]
	v_ashrrev_i32_e32 v129, 4, v128
	v_and_b32_e32 v130, 0x7ff, v128
	v_and_b32_e32 v129, 0xffffff80, v129
	s_movk_i32 s4, 0xf880
	ds_read_b32 v138, v165 offset:192
	v_and_b32_e32 v132, 63, v128
	v_cmp_lt_u32_e64 s[0:1], s0, v130
	v_add3_u32 v130, v130, v129, s4
	v_lshlrev_b32_e32 v128, 1, v128
	s_movk_i32 s4, 0xff80
	v_and_or_b32 v128, v128, s4, v132
	v_add_u32_e32 v128, 0xffff8040, v128
	v_ashrrev_i32_e32 v129, 31, v128
	v_lshl_add_u64 v[174:175], v[140:141], 0, v[156:157]
	v_lshlrev_b64 v[128:129], 9, v[128:129]
	v_lshl_add_u64 v[172:173], s[30:31], 0, v[128:129]
	s_waitcnt lgkmcnt(0)
	v_pk_mul_f32 v[128:129], v[76:77], v[138:139] op_sel_hi:[1,0]
	v_pk_mul_f32 v[132:133], v[72:73], v[138:139] op_sel_hi:[1,0]
	v_ashrrev_i32_e32 v131, 31, v130
	v_lshlrev_b64 v[130:131], 9, v[130:131]
	s_nop 0
	v_lshl_add_u64 v[142:143], s[26:27], 0, v[130:131]
	v_pk_mul_f32 v[130:131], v[78:79], v[138:139] op_sel_hi:[1,0]
	v_pk_mul_f32 v[134:135], v[74:75], v[138:139] op_sel_hi:[1,0]
	s_or_b64 s[0:1], s[38:39], s[0:1]
	s_nop 0
	v_cndmask_b32_e64 v143, v143, v173, s[38:39]
	s_nop 0
	v_cndmask_b32_e64 v142, v142, v172, s[38:39]
	s_nop 0
	v_cvt_pk_bf16_f32 v190, v128, v129
	v_cvt_pk_bf16_f32 v191, v130, v131
	v_cvt_pk_bf16_f32 v217, v132, v133
	v_cvt_pk_bf16_f32 v226, v134, v135
	v_add_co_u32_e32 v174, vcc, v223, v174
	s_nop 1
	v_addc_co_u32_e32 v175, vcc, 0, v175, vcc
	v_mov_b32_dpp v250, v190 quad_perm:[1,0,3,2] row_mask:0xf bank_mask:0xf
	v_perm_b32 v190, v250, v190, v220
	global_store_dword v[174:175], v190, off
	s_mov_b32 s100, 0x12000
	v_lshl_add_u64 v[176:177], v[174:175], 0, s[100:101]
	v_mov_b32_dpp v250, v191 quad_perm:[1,0,3,2] row_mask:0xf bank_mask:0xf
	v_perm_b32 v191, v250, v191, v220
	global_store_dword v[176:177], v191, off
	s_mov_b32 s100, 0x24000
	v_lshl_add_u64 v[176:177], v[174:175], 0, s[100:101]
	v_mov_b32_dpp v250, v217 quad_perm:[1,0,3,2] row_mask:0xf bank_mask:0xf
	v_perm_b32 v217, v250, v217, v220
	global_store_dword v[176:177], v217, off
	s_mov_b32 s100, 0x36000
	v_lshl_add_u64 v[176:177], v[174:175], 0, s[100:101]
	v_mov_b32_dpp v250, v226 quad_perm:[1,0,3,2] row_mask:0xf bank_mask:0xf
	v_perm_b32 v226, v250, v226, v220
	global_store_dword v[176:177], v226, off
	s_and_saveexec_b64 s[4:5], s[0:1]
	s_cbranch_execz .LBB0_641
	v_lshl_add_u64 v[172:173], v[142:143], 0, v[184:185]
	global_store_dwordx4 v[172:173], v[128:131], off offset:-512 nt
	global_store_dwordx4 v[172:173], v[132:135], off offset:-496 nt
.LBB0_641:
	s_or_b64 exec, exec, s[4:5]
	v_mov_b32_e32 v139, v138
	v_mov_b32_e32 v132, v138
	v_mov_b32_e32 v133, v138
	v_pk_mul_f32 v[130:131], v[70:71], v[132:133]
	v_pk_mul_f32 v[128:129], v[68:69], v[138:139]
	v_pk_mul_f32 v[134:135], v[66:67], v[132:133]
	v_pk_mul_f32 v[132:133], v[64:65], v[138:139]
	v_lshl_add_u64 v[138:139], v[140:141], 0, v[158:159]
	s_nop 1
	s_nop 1
	s_nop 0
	v_cvt_pk_bf16_f32 v190, v128, v129
	v_cvt_pk_bf16_f32 v191, v130, v131
	v_cvt_pk_bf16_f32 v217, v132, v133
	v_cvt_pk_bf16_f32 v226, v134, v135
	v_add_co_u32_e32 v138, vcc, v223, v138
	s_nop 1
	v_addc_co_u32_e32 v139, vcc, 0, v139, vcc
	v_mov_b32_dpp v250, v190 quad_perm:[1,0,3,2] row_mask:0xf bank_mask:0xf
	v_perm_b32 v190, v250, v190, v220
	global_store_dword v[138:139], v190, off
	s_mov_b32 s100, 0x12000
	v_lshl_add_u64 v[140:141], v[138:139], 0, s[100:101]
	v_mov_b32_dpp v250, v191 quad_perm:[1,0,3,2] row_mask:0xf bank_mask:0xf
	v_perm_b32 v191, v250, v191, v220
	global_store_dword v[140:141], v191, off
	s_mov_b32 s100, 0x24000
	v_lshl_add_u64 v[140:141], v[138:139], 0, s[100:101]
	v_mov_b32_dpp v250, v217 quad_perm:[1,0,3,2] row_mask:0xf bank_mask:0xf
	v_perm_b32 v217, v250, v217, v220
	global_store_dword v[140:141], v217, off
	s_mov_b32 s100, 0x36000
	v_lshl_add_u64 v[140:141], v[138:139], 0, s[100:101]
	v_mov_b32_dpp v250, v226 quad_perm:[1,0,3,2] row_mask:0xf bank_mask:0xf
	v_perm_b32 v226, v250, v226, v220
	global_store_dword v[140:141], v226, off
	s_and_saveexec_b64 s[4:5], s[0:1]
	s_cbranch_execz .LBB0_643
	v_mov_b32_e32 v137, v185
	v_lshl_add_u64 v[138:139], v[142:143], 0, v[136:137]
	global_store_dwordx4 v[138:139], v[128:131], off offset:-512 nt
	global_store_dwordx4 v[138:139], v[132:135], off offset:-496 nt
; __device__ __forceinline__ bf16_t f2bf1(float f) { return (bf16_t)(cvt_pk_bf16(f, 0.f) & 0xffffu); }
;     __device__ __forceinline__ void operator()(const f32x4 (&acc)[2][2][4][2], const Unit& u, int wr, int wc, int fr, int fq) const {
;     ...
;         } else if (pn == 2) {
;             bf16_t* VTG = (bf16_t*)(ws + WS_VTG);
;             float* ovp = out + O_WVP + (size_t)l * 131072; float* ovs = out + O_WVS + (size_t)l * 524288;
; #pragma unroll
;             for (int ai = 0; ai < 2; ++ai)
; #pragma unroll
;                 for (int m = 0; m < 4; ++m) {
;                     int row = u.pm * BM + ai * HALF + wr * 64 + m * 16 + fr;
;                     asm volatile("" : "+v"(row));
;                     const float rs = R[ai * HALF + wr * 64 + m * 16 + fr];
;                     const int sb = (row - E_MP) >> 6, st = (row - E_MP) & 63, pb = row >> 11, pt = row & 2047;
; #pragma unroll
;                     for (int bj = 0; bj < 2; ++bj) {
;                         const f32x4 v0 = acc[ai][bj][m][0] * rs, v1 = acc[ai][bj][m][1] * rs;
;                         const int c0 = (wc - 2) * 64 + bj * 32 + 8 * fq;
;                         bf16_t* vp = VTG + (size_t)c0 * E_MT + row;
; #pragma unroll
;                         for (int j = 0; j < 4; ++j) { vp[(size_t)j * E_MT] = f2bf1(v0[j]); vp[(size_t)(4 + j) * E_MT] = f2bf1(v1[j]); }
;                         if (is_s) { float* d = ovs + ((size_t)(sb * 128 + 64 + st) * 128 + c0); __builtin_nontemporal_store(v0, (f32x4*)d); __builtin_nontemporal_store(v1, (f32x4*)(d + 4)); }
;                         else if (pt >= 1920) { float* d = ovp + ((size_t)(pb * 128 + (pt - 1920)) * 128 + c0); __builtin_nontemporal_store(v0, (f32x4*)d); __builtin_nontemporal_store(v1, (f32x4*)(d + 4)); }
;                     }
;                 }
.LBB0_643:
	s_or_b64 exec, exec, s[4:5]
	v_add_u32_e32 v128, 0x80, v170
	s_movk_i32 s0, 0x77f
	v_ashrrev_i32_e32 v129, 31, v128
	v_lshl_add_u64 v[140:141], v[128:129], 1, s[42:43]
	v_ashrrev_i32_e32 v129, 4, v128
	v_and_b32_e32 v130, 0x7ff, v128
	v_and_b32_e32 v129, 0xffffff80, v129
	s_movk_i32 s4, 0xf880
	ds_read_b32 v138, v165 offset:512
	v_and_b32_e32 v132, 63, v128
	v_cmp_lt_u32_e64 s[0:1], s0, v130
	v_add3_u32 v130, v130, v129, s4
	v_lshlrev_b32_e32 v128, 1, v128
	s_movk_i32 s4, 0xff80
	v_and_or_b32 v128, v128, s4, v132
	v_add_u32_e32 v128, 0xffff8040, v128
	v_ashrrev_i32_e32 v129, 31, v128
	v_lshl_add_u64 v[174:175], v[140:141], 0, v[156:157]
	v_lshlrev_b64 v[128:129], 9, v[128:129]
	v_lshl_add_u64 v[172:173], s[30:31], 0, v[128:129]
	s_waitcnt lgkmcnt(0)
	v_pk_mul_f32 v[128:129], v[60:61], v[138:139] op_sel_hi:[1,0]
	v_pk_mul_f32 v[132:133], v[56:57], v[138:139] op_sel_hi:[1,0]
	v_ashrrev_i32_e32 v131, 31, v130
	v_lshlrev_b64 v[130:131], 9, v[130:131]
	s_nop 0
	v_lshl_add_u64 v[142:143], s[26:27], 0, v[130:131]
	v_pk_mul_f32 v[130:131], v[62:63], v[138:139] op_sel_hi:[1,0]
	v_pk_mul_f32 v[134:135], v[58:59], v[138:139] op_sel_hi:[1,0]
	s_or_b64 s[0:1], s[38:39], s[0:1]
	s_nop 0
	v_cndmask_b32_e64 v143, v143, v173, s[38:39]
	s_nop 0
	v_cndmask_b32_e64 v142, v142, v172, s[38:39]
	s_nop 0
	v_cvt_pk_bf16_f32 v190, v128, v129
	v_cvt_pk_bf16_f32 v191, v130, v131
	v_cvt_pk_bf16_f32 v217, v132, v133
	v_cvt_pk_bf16_f32 v226, v134, v135
	v_add_co_u32_e32 v174, vcc, v223, v174
	s_nop 1
	v_addc_co_u32_e32 v175, vcc, 0, v175, vcc
	v_mov_b32_dpp v250, v190 quad_perm:[1,0,3,2] row_mask:0xf bank_mask:0xf
	v_perm_b32 v190, v250, v190, v220
	global_store_dword v[174:175], v190, off
	s_mov_b32 s100, 0x12000
	v_lshl_add_u64 v[176:177], v[174:175], 0, s[100:101]
	v_mov_b32_dpp v250, v191 quad_perm:[1,0,3,2] row_mask:0xf bank_mask:0xf
	v_perm_b32 v191, v250, v191, v220
	global_store_dword v[176:177], v191, off
	s_mov_b32 s100, 0x24000
	v_lshl_add_u64 v[176:177], v[174:175], 0, s[100:101]
	v_mov_b32_dpp v250, v217 quad_perm:[1,0,3,2] row_mask:0xf bank_mask:0xf
	v_perm_b32 v217, v250, v217, v220
	global_store_dword v[176:177], v217, off
	s_mov_b32 s100, 0x36000
	v_lshl_add_u64 v[176:177], v[174:175], 0, s[100:101]
	v_mov_b32_dpp v250, v226 quad_perm:[1,0,3,2] row_mask:0xf bank_mask:0xf
	v_perm_b32 v226, v250, v226, v220
	global_store_dword v[176:177], v226, off
	s_and_saveexec_b64 s[4:5], s[0:1]
	s_cbranch_execz .LBB0_645
	v_lshl_add_u64 v[172:173], v[142:143], 0, v[184:185]
	global_store_dwordx4 v[172:173], v[128:131], off offset:-512 nt
	global_store_dwordx4 v[172:173], v[132:135], off offset:-496 nt
.LBB0_645:
	s_or_b64 exec, exec, s[4:5]
	v_mov_b32_e32 v139, v138
	v_mov_b32_e32 v132, v138
	v_mov_b32_e32 v133, v138
	v_pk_mul_f32 v[130:131], v[54:55], v[132:133]
	v_pk_mul_f32 v[128:129], v[52:53], v[138:139]
	v_pk_mul_f32 v[134:135], v[50:51], v[132:133]
	v_pk_mul_f32 v[132:133], v[48:49], v[138:139]
	v_lshl_add_u64 v[138:139], v[140:141], 0, v[158:159]
	s_nop 1
	s_nop 1
	s_nop 0
	v_cvt_pk_bf16_f32 v190, v128, v129
	v_cvt_pk_bf16_f32 v191, v130, v131
	v_cvt_pk_bf16_f32 v217, v132, v133
	v_cvt_pk_bf16_f32 v226, v134, v135
	v_add_co_u32_e32 v138, vcc, v223, v138
	s_nop 1
	v_addc_co_u32_e32 v139, vcc, 0, v139, vcc
	v_mov_b32_dpp v250, v190 quad_perm:[1,0,3,2] row_mask:0xf bank_mask:0xf
	v_perm_b32 v190, v250, v190, v220
	global_store_dword v[138:139], v190, off
	s_mov_b32 s100, 0x12000
	v_lshl_add_u64 v[140:141], v[138:139], 0, s[100:101]
	v_mov_b32_dpp v250, v191 quad_perm:[1,0,3,2] row_mask:0xf bank_mask:0xf
	v_perm_b32 v191, v250, v191, v220
	global_store_dword v[140:141], v191, off
	s_mov_b32 s100, 0x24000
	v_lshl_add_u64 v[140:141], v[138:139], 0, s[100:101]
	v_mov_b32_dpp v250, v217 quad_perm:[1,0,3,2] row_mask:0xf bank_mask:0xf
	v_perm_b32 v217, v250, v217, v220
	global_store_dword v[140:141], v217, off
	s_mov_b32 s100, 0x36000
	v_lshl_add_u64 v[140:141], v[138:139], 0, s[100:101]
	v_mov_b32_dpp v250, v226 quad_perm:[1,0,3,2] row_mask:0xf bank_mask:0xf
	v_perm_b32 v226, v250, v226, v220
	global_store_dword v[140:141], v226, off
	s_and_saveexec_b64 s[4:5], s[0:1]
	s_cbranch_execz .LBB0_647
	v_mov_b32_e32 v137, v185
	v_lshl_add_u64 v[138:139], v[142:143], 0, v[136:137]
	global_store_dwordx4 v[138:139], v[128:131], off offset:-512 nt
	global_store_dwordx4 v[138:139], v[132:135], off offset:-496 nt
; __device__ __forceinline__ bf16_t f2bf1(float f) { return (bf16_t)(cvt_pk_bf16(f, 0.f) & 0xffffu); }
;     __device__ __forceinline__ void operator()(const f32x4 (&acc)[2][2][4][2], const Unit& u, int wr, int wc, int fr, int fq) const {
;     ...
;         } else if (pn == 2) {
;             bf16_t* VTG = (bf16_t*)(ws + WS_VTG);
;             float* ovp = out + O_WVP + (size_t)l * 131072; float* ovs = out + O_WVS + (size_t)l * 524288;
; #pragma unroll
;             for (int ai = 0; ai < 2; ++ai)
; #pragma unroll
;                 for (int m = 0; m < 4; ++m) {
;                     int row = u.pm * BM + ai * HALF + wr * 64 + m * 16 + fr;
;                     asm volatile("" : "+v"(row));
;                     const float rs = R[ai * HALF + wr * 64 + m * 16 + fr];
;                     const int sb = (row - E_MP) >> 6, st = (row - E_MP) & 63, pb = row >> 11, pt = row & 2047;
; #pragma unroll
;                     for (int bj = 0; bj < 2; ++bj) {
;                         const f32x4 v0 = acc[ai][bj][m][0] * rs, v1 = acc[ai][bj][m][1] * rs;
;                         const int c0 = (wc - 2) * 64 + bj * 32 + 8 * fq;
;                         bf16_t* vp = VTG + (size_t)c0 * E_MT + row;
; #pragma unroll
;                         for (int j = 0; j < 4; ++j) { vp[(size_t)j * E_MT] = f2bf1(v0[j]); vp[(size_t)(4 + j) * E_MT] = f2bf1(v1[j]); }
;                         if (is_s) { float* d = ovs + ((size_t)(sb * 128 + 64 + st) * 128 + c0); __builtin_nontemporal_store(v0, (f32x4*)d); __builtin_nontemporal_store(v1, (f32x4*)(d + 4)); }
;                         else if (pt >= 1920) { float* d = ovp + ((size_t)(pb * 128 + (pt - 1920)) * 128 + c0); __builtin_nontemporal_store(v0, (f32x4*)d); __builtin_nontemporal_store(v1, (f32x4*)(d + 4)); }
;                     }
;                 }
.LBB0_647:
	s_or_b64 exec, exec, s[4:5]
	v_add_u32_e32 v128, 0x90, v170
	s_movk_i32 s0, 0x77f
	v_ashrrev_i32_e32 v129, 31, v128
	v_lshl_add_u64 v[140:141], v[128:129], 1, s[42:43]
	v_ashrrev_i32_e32 v129, 4, v128
	v_and_b32_e32 v130, 0x7ff, v128
	v_and_b32_e32 v129, 0xffffff80, v129
	s_movk_i32 s4, 0xf880
	ds_read_b32 v138, v165 offset:576
	v_and_b32_e32 v132, 63, v128
	v_cmp_lt_u32_e64 s[0:1], s0, v130
	v_add3_u32 v130, v130, v129, s4
	v_lshlrev_b32_e32 v128, 1, v128
	s_movk_i32 s4, 0xff80
	v_and_or_b32 v128, v128, s4, v132
	v_add_u32_e32 v128, 0xffff8040, v128
	v_ashrrev_i32_e32 v129, 31, v128
	v_lshl_add_u64 v[174:175], v[140:141], 0, v[156:157]
	v_lshlrev_b64 v[128:129], 9, v[128:129]
	v_lshl_add_u64 v[172:173], s[30:31], 0, v[128:129]
	s_waitcnt lgkmcnt(0)
	v_pk_mul_f32 v[128:129], v[44:45], v[138:139] op_sel_hi:[1,0]
	v_pk_mul_f32 v[132:133], v[40:41], v[138:139] op_sel_hi:[1,0]
	v_ashrrev_i32_e32 v131, 31, v130
	v_lshlrev_b64 v[130:131], 9, v[130:131]
	s_nop 0
	v_lshl_add_u64 v[142:143], s[26:27], 0, v[130:131]
	v_pk_mul_f32 v[130:131], v[46:47], v[138:139] op_sel_hi:[1,0]
	v_pk_mul_f32 v[134:135], v[42:43], v[138:139] op_sel_hi:[1,0]
	s_or_b64 s[0:1], s[38:39], s[0:1]
	s_nop 0
	v_cndmask_b32_e64 v143, v143, v173, s[38:39]
	s_nop 0
	v_cndmask_b32_e64 v142, v142, v172, s[38:39]
	s_nop 0
	v_cvt_pk_bf16_f32 v190, v128, v129
	v_cvt_pk_bf16_f32 v191, v130, v131
	v_cvt_pk_bf16_f32 v217, v132, v133
	v_cvt_pk_bf16_f32 v226, v134, v135
	v_add_co_u32_e32 v174, vcc, v223, v174
	s_nop 1
	v_addc_co_u32_e32 v175, vcc, 0, v175, vcc
	v_mov_b32_dpp v250, v190 quad_perm:[1,0,3,2] row_mask:0xf bank_mask:0xf
	v_perm_b32 v190, v250, v190, v220
	global_store_dword v[174:175], v190, off
	s_mov_b32 s100, 0x12000
	v_lshl_add_u64 v[176:177], v[174:175], 0, s[100:101]
	v_mov_b32_dpp v250, v191 quad_perm:[1,0,3,2] row_mask:0xf bank_mask:0xf
	v_perm_b32 v191, v250, v191, v220
	global_store_dword v[176:177], v191, off
	s_mov_b32 s100, 0x24000
	v_lshl_add_u64 v[176:177], v[174:175], 0, s[100:101]
	v_mov_b32_dpp v250, v217 quad_perm:[1,0,3,2] row_mask:0xf bank_mask:0xf
	v_perm_b32 v217, v250, v217, v220
	global_store_dword v[176:177], v217, off
	s_mov_b32 s100, 0x36000
	v_lshl_add_u64 v[176:177], v[174:175], 0, s[100:101]
	v_mov_b32_dpp v250, v226 quad_perm:[1,0,3,2] row_mask:0xf bank_mask:0xf
	v_perm_b32 v226, v250, v226, v220
	global_store_dword v[176:177], v226, off
	s_and_saveexec_b64 s[4:5], s[0:1]
	s_cbranch_execz .LBB0_649
	v_lshl_add_u64 v[172:173], v[142:143], 0, v[184:185]
	global_store_dwordx4 v[172:173], v[128:131], off offset:-512 nt
	global_store_dwordx4 v[172:173], v[132:135], off offset:-496 nt
.LBB0_649:
	s_or_b64 exec, exec, s[4:5]
	v_mov_b32_e32 v139, v138
	v_mov_b32_e32 v132, v138
	v_mov_b32_e32 v133, v138
	v_pk_mul_f32 v[130:131], v[38:39], v[132:133]
	v_pk_mul_f32 v[128:129], v[36:37], v[138:139]
	v_pk_mul_f32 v[134:135], v[34:35], v[132:133]
	v_pk_mul_f32 v[132:133], v[32:33], v[138:139]
	v_lshl_add_u64 v[138:139], v[140:141], 0, v[158:159]
	s_nop 1
	s_nop 1
	s_nop 0
	v_cvt_pk_bf16_f32 v190, v128, v129
	v_cvt_pk_bf16_f32 v191, v130, v131
	v_cvt_pk_bf16_f32 v217, v132, v133
	v_cvt_pk_bf16_f32 v226, v134, v135
	v_add_co_u32_e32 v138, vcc, v223, v138
	s_nop 1
	v_addc_co_u32_e32 v139, vcc, 0, v139, vcc
	v_mov_b32_dpp v250, v190 quad_perm:[1,0,3,2] row_mask:0xf bank_mask:0xf
	v_perm_b32 v190, v250, v190, v220
	global_store_dword v[138:139], v190, off
	s_mov_b32 s100, 0x12000
	v_lshl_add_u64 v[140:141], v[138:139], 0, s[100:101]
	v_mov_b32_dpp v250, v191 quad_perm:[1,0,3,2] row_mask:0xf bank_mask:0xf
	v_perm_b32 v191, v250, v191, v220
	global_store_dword v[140:141], v191, off
	s_mov_b32 s100, 0x24000
	v_lshl_add_u64 v[140:141], v[138:139], 0, s[100:101]
	v_mov_b32_dpp v250, v217 quad_perm:[1,0,3,2] row_mask:0xf bank_mask:0xf
	v_perm_b32 v217, v250, v217, v220
	global_store_dword v[140:141], v217, off
	s_mov_b32 s100, 0x36000
	v_lshl_add_u64 v[140:141], v[138:139], 0, s[100:101]
	v_mov_b32_dpp v250, v226 quad_perm:[1,0,3,2] row_mask:0xf bank_mask:0xf
	v_perm_b32 v226, v250, v226, v220
	global_store_dword v[140:141], v226, off
	s_and_saveexec_b64 s[4:5], s[0:1]
	s_cbranch_execz .LBB0_651
	v_mov_b32_e32 v137, v185
	v_lshl_add_u64 v[138:139], v[142:143], 0, v[136:137]
	global_store_dwordx4 v[138:139], v[128:131], off offset:-512 nt
	global_store_dwordx4 v[138:139], v[132:135], off offset:-496 nt
; __device__ __forceinline__ bf16_t f2bf1(float f) { return (bf16_t)(cvt_pk_bf16(f, 0.f) & 0xffffu); }
;     __device__ __forceinline__ void operator()(const f32x4 (&acc)[2][2][4][2], const Unit& u, int wr, int wc, int fr, int fq) const {
;     ...
;         } else if (pn == 2) {
;             bf16_t* VTG = (bf16_t*)(ws + WS_VTG);
;             float* ovp = out + O_WVP + (size_t)l * 131072; float* ovs = out + O_WVS + (size_t)l * 524288;
; #pragma unroll
;             for (int ai = 0; ai < 2; ++ai)
; #pragma unroll
;                 for (int m = 0; m < 4; ++m) {
;                     int row = u.pm * BM + ai * HALF + wr * 64 + m * 16 + fr;
;                     asm volatile("" : "+v"(row));
;                     const float rs = R[ai * HALF + wr * 64 + m * 16 + fr];
;                     const int sb = (row - E_MP) >> 6, st = (row - E_MP) & 63, pb = row >> 11, pt = row & 2047;
; #pragma unroll
;                     for (int bj = 0; bj < 2; ++bj) {
;                         const f32x4 v0 = acc[ai][bj][m][0] * rs, v1 = acc[ai][bj][m][1] * rs;
;                         const int c0 = (wc - 2) * 64 + bj * 32 + 8 * fq;
;                         bf16_t* vp = VTG + (size_t)c0 * E_MT + row;
; #pragma unroll
;                         for (int j = 0; j < 4; ++j) { vp[(size_t)j * E_MT] = f2bf1(v0[j]); vp[(size_t)(4 + j) * E_MT] = f2bf1(v1[j]); }
;                         if (is_s) { float* d = ovs + ((size_t)(sb * 128 + 64 + st) * 128 + c0); __builtin_nontemporal_store(v0, (f32x4*)d); __builtin_nontemporal_store(v1, (f32x4*)(d + 4)); }
;                         else if (pt >= 1920) { float* d = ovp + ((size_t)(pb * 128 + (pt - 1920)) * 128 + c0); __builtin_nontemporal_store(v0, (f32x4*)d); __builtin_nontemporal_store(v1, (f32x4*)(d + 4)); }
;                     }
;                 }
.LBB0_651:
	s_or_b64 exec, exec, s[4:5]
	v_add_u32_e32 v128, 0xa0, v170
	s_movk_i32 s0, 0x77f
	v_ashrrev_i32_e32 v129, 31, v128
	v_lshl_add_u64 v[140:141], v[128:129], 1, s[42:43]
	v_ashrrev_i32_e32 v129, 4, v128
	v_and_b32_e32 v130, 0x7ff, v128
	v_and_b32_e32 v129, 0xffffff80, v129
	s_movk_i32 s4, 0xf880
	ds_read_b32 v138, v165 offset:640
	v_and_b32_e32 v132, 63, v128
	v_cmp_lt_u32_e64 s[0:1], s0, v130
	v_add3_u32 v130, v130, v129, s4
	v_lshlrev_b32_e32 v128, 1, v128
	s_movk_i32 s4, 0xff80
	v_and_or_b32 v128, v128, s4, v132
	v_add_u32_e32 v128, 0xffff8040, v128
	v_ashrrev_i32_e32 v129, 31, v128
	v_lshl_add_u64 v[174:175], v[140:141], 0, v[156:157]
	v_lshlrev_b64 v[128:129], 9, v[128:129]
	v_lshl_add_u64 v[172:173], s[30:31], 0, v[128:129]
	s_waitcnt lgkmcnt(0)
	v_pk_mul_f32 v[128:129], v[28:29], v[138:139] op_sel_hi:[1,0]
	v_pk_mul_f32 v[132:133], v[24:25], v[138:139] op_sel_hi:[1,0]
	v_ashrrev_i32_e32 v131, 31, v130
	v_lshlrev_b64 v[130:131], 9, v[130:131]
	s_nop 0
	v_lshl_add_u64 v[142:143], s[26:27], 0, v[130:131]
	v_pk_mul_f32 v[130:131], v[30:31], v[138:139] op_sel_hi:[1,0]
	v_pk_mul_f32 v[134:135], v[26:27], v[138:139] op_sel_hi:[1,0]
	s_or_b64 s[0:1], s[38:39], s[0:1]
	s_nop 0
	v_cndmask_b32_e64 v143, v143, v173, s[38:39]
	s_nop 0
	v_cndmask_b32_e64 v142, v142, v172, s[38:39]
	s_nop 0
	v_cvt_pk_bf16_f32 v190, v128, v129
	v_cvt_pk_bf16_f32 v191, v130, v131
	v_cvt_pk_bf16_f32 v217, v132, v133
	v_cvt_pk_bf16_f32 v226, v134, v135
	v_add_co_u32_e32 v174, vcc, v223, v174
	s_nop 1
	v_addc_co_u32_e32 v175, vcc, 0, v175, vcc
	v_mov_b32_dpp v250, v190 quad_perm:[1,0,3,2] row_mask:0xf bank_mask:0xf
	v_perm_b32 v190, v250, v190, v220
	global_store_dword v[174:175], v190, off
	s_mov_b32 s100, 0x12000
	v_lshl_add_u64 v[176:177], v[174:175], 0, s[100:101]
	v_mov_b32_dpp v250, v191 quad_perm:[1,0,3,2] row_mask:0xf bank_mask:0xf
	v_perm_b32 v191, v250, v191, v220
	global_store_dword v[176:177], v191, off
	s_mov_b32 s100, 0x24000
	v_lshl_add_u64 v[176:177], v[174:175], 0, s[100:101]
	v_mov_b32_dpp v250, v217 quad_perm:[1,0,3,2] row_mask:0xf bank_mask:0xf
	v_perm_b32 v217, v250, v217, v220
	global_store_dword v[176:177], v217, off
	s_mov_b32 s100, 0x36000
	v_lshl_add_u64 v[176:177], v[174:175], 0, s[100:101]
	v_mov_b32_dpp v250, v226 quad_perm:[1,0,3,2] row_mask:0xf bank_mask:0xf
	v_perm_b32 v226, v250, v226, v220
	global_store_dword v[176:177], v226, off
	s_and_saveexec_b64 s[4:5], s[0:1]
	s_cbranch_execz .LBB0_653
	v_lshl_add_u64 v[172:173], v[142:143], 0, v[184:185]
	global_store_dwordx4 v[172:173], v[128:131], off offset:-512 nt
	global_store_dwordx4 v[172:173], v[132:135], off offset:-496 nt
.LBB0_653:
	s_or_b64 exec, exec, s[4:5]
	v_mov_b32_e32 v139, v138
	v_mov_b32_e32 v132, v138
	v_mov_b32_e32 v133, v138
	v_pk_mul_f32 v[130:131], v[22:23], v[132:133]
	v_pk_mul_f32 v[128:129], v[20:21], v[138:139]
	v_pk_mul_f32 v[134:135], v[18:19], v[132:133]
	v_pk_mul_f32 v[132:133], v[16:17], v[138:139]
	v_lshl_add_u64 v[138:139], v[140:141], 0, v[158:159]
	s_nop 1
	s_nop 1
	s_nop 0
	v_cvt_pk_bf16_f32 v190, v128, v129
	v_cvt_pk_bf16_f32 v191, v130, v131
	v_cvt_pk_bf16_f32 v217, v132, v133
	v_cvt_pk_bf16_f32 v226, v134, v135
	v_add_co_u32_e32 v138, vcc, v223, v138
	s_nop 1
	v_addc_co_u32_e32 v139, vcc, 0, v139, vcc
	v_mov_b32_dpp v250, v190 quad_perm:[1,0,3,2] row_mask:0xf bank_mask:0xf
	v_perm_b32 v190, v250, v190, v220
	global_store_dword v[138:139], v190, off
	s_mov_b32 s100, 0x12000
	v_lshl_add_u64 v[140:141], v[138:139], 0, s[100:101]
	v_mov_b32_dpp v250, v191 quad_perm:[1,0,3,2] row_mask:0xf bank_mask:0xf
	v_perm_b32 v191, v250, v191, v220
	global_store_dword v[140:141], v191, off
	s_mov_b32 s100, 0x24000
	v_lshl_add_u64 v[140:141], v[138:139], 0, s[100:101]
	v_mov_b32_dpp v250, v217 quad_perm:[1,0,3,2] row_mask:0xf bank_mask:0xf
	v_perm_b32 v217, v250, v217, v220
	global_store_dword v[140:141], v217, off
	s_mov_b32 s100, 0x36000
	v_lshl_add_u64 v[140:141], v[138:139], 0, s[100:101]
	v_mov_b32_dpp v250, v226 quad_perm:[1,0,3,2] row_mask:0xf bank_mask:0xf
	v_perm_b32 v226, v250, v226, v220
	global_store_dword v[140:141], v226, off
	s_and_saveexec_b64 s[4:5], s[0:1]
	s_cbranch_execz .LBB0_655
	v_mov_b32_e32 v137, v185
	v_lshl_add_u64 v[138:139], v[142:143], 0, v[136:137]
	global_store_dwordx4 v[138:139], v[128:131], off offset:-512 nt
	global_store_dwordx4 v[138:139], v[132:135], off offset:-496 nt
; __device__ __forceinline__ bf16_t f2bf1(float f) { return (bf16_t)(cvt_pk_bf16(f, 0.f) & 0xffffu); }
;     __device__ __forceinline__ void operator()(const f32x4 (&acc)[2][2][4][2], const Unit& u, int wr, int wc, int fr, int fq) const {
;     ...
;         } else if (pn == 2) {
;             bf16_t* VTG = (bf16_t*)(ws + WS_VTG);
;             float* ovp = out + O_WVP + (size_t)l * 131072; float* ovs = out + O_WVS + (size_t)l * 524288;
; #pragma unroll
;             for (int ai = 0; ai < 2; ++ai)
; #pragma unroll
;                 for (int m = 0; m < 4; ++m) {
;                     int row = u.pm * BM + ai * HALF + wr * 64 + m * 16 + fr;
;                     asm volatile("" : "+v"(row));
;                     const float rs = R[ai * HALF + wr * 64 + m * 16 + fr];
;                     const int sb = (row - E_MP) >> 6, st = (row - E_MP) & 63, pb = row >> 11, pt = row & 2047;
; #pragma unroll
;                     for (int bj = 0; bj < 2; ++bj) {
;                         const f32x4 v0 = acc[ai][bj][m][0] * rs, v1 = acc[ai][bj][m][1] * rs;
;                         const int c0 = (wc - 2) * 64 + bj * 32 + 8 * fq;
;                         bf16_t* vp = VTG + (size_t)c0 * E_MT + row;
; #pragma unroll
;                         for (int j = 0; j < 4; ++j) { vp[(size_t)j * E_MT] = f2bf1(v0[j]); vp[(size_t)(4 + j) * E_MT] = f2bf1(v1[j]); }
;                         if (is_s) { float* d = ovs + ((size_t)(sb * 128 + 64 + st) * 128 + c0); __builtin_nontemporal_store(v0, (f32x4*)d); __builtin_nontemporal_store(v1, (f32x4*)(d + 4)); }
;                         else if (pt >= 1920) { float* d = ovp + ((size_t)(pb * 128 + (pt - 1920)) * 128 + c0); __builtin_nontemporal_store(v0, (f32x4*)d); __builtin_nontemporal_store(v1, (f32x4*)(d + 4)); }
;                     }
;                 }
.LBB0_655:
	s_or_b64 exec, exec, s[4:5]
	v_add_u32_e32 v128, 0xb0, v170
	s_movk_i32 s0, 0x77f
	v_ashrrev_i32_e32 v129, 31, v128
	v_lshl_add_u64 v[140:141], v[128:129], 1, s[42:43]
	v_ashrrev_i32_e32 v129, 4, v128
	v_and_b32_e32 v130, 0x7ff, v128
	v_and_b32_e32 v129, 0xffffff80, v129
	s_movk_i32 s4, 0xf880
	ds_read_b32 v138, v165 offset:704
	v_and_b32_e32 v132, 63, v128
	v_cmp_lt_u32_e64 s[0:1], s0, v130
	v_add3_u32 v130, v130, v129, s4
	v_lshlrev_b32_e32 v128, 1, v128
	s_movk_i32 s4, 0xff80
	v_and_or_b32 v128, v128, s4, v132
	v_add_u32_e32 v128, 0xffff8040, v128
	v_ashrrev_i32_e32 v129, 31, v128
	v_lshl_add_u64 v[172:173], v[140:141], 0, v[156:157]
	v_lshlrev_b64 v[128:129], 9, v[128:129]
	v_lshl_add_u64 v[170:171], s[30:31], 0, v[128:129]
	s_waitcnt lgkmcnt(0)
	v_pk_mul_f32 v[128:129], v[12:13], v[138:139] op_sel_hi:[1,0]
	v_pk_mul_f32 v[132:133], v[8:9], v[138:139] op_sel_hi:[1,0]
	v_ashrrev_i32_e32 v131, 31, v130
	v_lshlrev_b64 v[130:131], 9, v[130:131]
	s_nop 0
	v_lshl_add_u64 v[142:143], s[26:27], 0, v[130:131]
	v_pk_mul_f32 v[130:131], v[14:15], v[138:139] op_sel_hi:[1,0]
	v_pk_mul_f32 v[134:135], v[10:11], v[138:139] op_sel_hi:[1,0]
	s_or_b64 s[0:1], s[38:39], s[0:1]
	s_nop 0
	v_cndmask_b32_e64 v143, v143, v171, s[38:39]
	s_nop 0
	v_cndmask_b32_e64 v142, v142, v170, s[38:39]
	s_nop 0
	v_cvt_pk_bf16_f32 v190, v128, v129
	v_cvt_pk_bf16_f32 v191, v130, v131
	v_cvt_pk_bf16_f32 v217, v132, v133
	v_cvt_pk_bf16_f32 v226, v134, v135
	v_add_co_u32_e32 v172, vcc, v223, v172
	s_nop 1
	v_addc_co_u32_e32 v173, vcc, 0, v173, vcc
	v_mov_b32_dpp v250, v190 quad_perm:[1,0,3,2] row_mask:0xf bank_mask:0xf
	v_perm_b32 v190, v250, v190, v220
	global_store_dword v[172:173], v190, off
	s_mov_b32 s100, 0x12000
	v_lshl_add_u64 v[174:175], v[172:173], 0, s[100:101]
	v_mov_b32_dpp v250, v191 quad_perm:[1,0,3,2] row_mask:0xf bank_mask:0xf
	v_perm_b32 v191, v250, v191, v220
	global_store_dword v[174:175], v191, off
	s_mov_b32 s100, 0x24000
	v_lshl_add_u64 v[174:175], v[172:173], 0, s[100:101]
	v_mov_b32_dpp v250, v217 quad_perm:[1,0,3,2] row_mask:0xf bank_mask:0xf
	v_perm_b32 v217, v250, v217, v220
	global_store_dword v[174:175], v217, off
	s_mov_b32 s100, 0x36000
	v_lshl_add_u64 v[174:175], v[172:173], 0, s[100:101]
	v_mov_b32_dpp v250, v226 quad_perm:[1,0,3,2] row_mask:0xf bank_mask:0xf
	v_perm_b32 v226, v250, v226, v220
	global_store_dword v[174:175], v226, off
	s_and_saveexec_b64 s[4:5], s[0:1]
	s_cbranch_execz .LBB0_657
	v_lshl_add_u64 v[170:171], v[142:143], 0, v[184:185]
	global_store_dwordx4 v[170:171], v[128:131], off offset:-512 nt
	global_store_dwordx4 v[170:171], v[132:135], off offset:-496 nt
.LBB0_657:
	s_or_b64 exec, exec, s[4:5]
	v_mov_b32_e32 v139, v138
	v_mov_b32_e32 v132, v138
	v_mov_b32_e32 v133, v138
	v_pk_mul_f32 v[130:131], v[6:7], v[132:133]
	v_pk_mul_f32 v[128:129], v[4:5], v[138:139]
	v_pk_mul_f32 v[134:135], v[2:3], v[132:133]
	v_pk_mul_f32 v[132:133], v[0:1], v[138:139]
	v_lshl_add_u64 v[138:139], v[140:141], 0, v[158:159]
	s_nop 1
	s_nop 1
	s_nop 0
	v_cvt_pk_bf16_f32 v190, v128, v129
	v_cvt_pk_bf16_f32 v191, v130, v131
	v_cvt_pk_bf16_f32 v217, v132, v133
	v_cvt_pk_bf16_f32 v226, v134, v135
	v_add_co_u32_e32 v138, vcc, v223, v138
	s_nop 1
	v_addc_co_u32_e32 v139, vcc, 0, v139, vcc
	v_mov_b32_dpp v250, v190 quad_perm:[1,0,3,2] row_mask:0xf bank_mask:0xf
	v_perm_b32 v190, v250, v190, v220
	global_store_dword v[138:139], v190, off
	s_mov_b32 s100, 0x12000
	v_lshl_add_u64 v[140:141], v[138:139], 0, s[100:101]
	v_mov_b32_dpp v250, v191 quad_perm:[1,0,3,2] row_mask:0xf bank_mask:0xf
	v_perm_b32 v191, v250, v191, v220
	global_store_dword v[140:141], v191, off
	s_mov_b32 s100, 0x24000
	v_lshl_add_u64 v[140:141], v[138:139], 0, s[100:101]
	v_mov_b32_dpp v250, v217 quad_perm:[1,0,3,2] row_mask:0xf bank_mask:0xf
	v_perm_b32 v217, v250, v217, v220
	global_store_dword v[140:141], v217, off
	s_mov_b32 s100, 0x36000
	v_lshl_add_u64 v[140:141], v[138:139], 0, s[100:101]
	v_mov_b32_dpp v250, v226 quad_perm:[1,0,3,2] row_mask:0xf bank_mask:0xf
	v_perm_b32 v226, v250, v226, v220
	global_store_dword v[140:141], v226, off
	s_and_saveexec_b64 s[4:5], s[0:1]
	s_cbranch_execz .LBB0_659
	v_mov_b32_e32 v137, v185
	v_lshl_add_u64 v[136:137], v[142:143], 0, v[136:137]
	global_store_dwordx4 v[136:137], v[128:131], off offset:-512 nt
	global_store_dwordx4 v[136:137], v[132:135], off offset:-496 nt
